# retention state chain: LDS-DMA touch loads of the K^T/V^T fragments two chunks ahead (besides the 1-ahead register prefetch), step wait vmcnt(4)->vmcnt(6), bit-identical
# baseline (speedup 1.0000x reference)
; DEV void phase_mix1(const Params& p, int l) {
;     ...
;   for (int it = blockIdx.x; it < 256; it += gridDim.x) chain_item(p, l, ok ? ((x * 4 + (j >> 3)) * 8 + (j & 7)) : it);
.LBB0_113:
	s_waitcnt vmcnt(0)
	s_add_i32 s20, s20, s74
	s_cmpk_gt_i32 s20, 0xff
	s_cbranch_scc1 .LBB0_118

; DEV float bf2f(u16 h) { return __uint_as_float(((unsigned)h) << 16); }
; DEV unsigned cvtpk(float lo, float hi) { unsigned r; asm("v_cvt_pk_bf16_f32 %0, %1, %2" : "=v"(r) : "v"(lo), "v"(hi)); return r; }
; DEV void chain_item(const Params& p, int l, int item) {
;     ...
;   for (int s = 0; s < 34; ++s) {
;     const int cid = (dir == 0) ? s : (s < 2 ? 1 - s : 35 - s);
;     bf16x8 kf[8], vf[8];
; #pragma unroll
;     for (int ks = 0; ks < 8; ++ks) { kf[ks] = kfn[ks]; vf[ks] = vfn[ks]; }
;     if (s + 1 < 34) { const int s1 = s + 1; const int cn = (dir == 0) ? s1 : (s1 < 2 ? 1 - s1 : 35 - s1);
; #pragma unroll
;       for (int ks = 0; ks < 8; ++ks) { kfn[ks] = *reinterpret_cast<const bf16x8*>(KTf + (size_t)cn * 32768 + ks * 512); vfn[ks] = *reinterpret_cast<const bf16x8*>(VTf + (size_t)cn * 32768 + ks * 512); } }
;     { u16* sp = ST + (size_t)cid * 65536 + ((size_t)(sl * 16 + 2 * wid) * 64 + r32) * 8 + 4 * hi;
; #pragma unroll
;       for (int q = 0; q < 4; ++q) {
;         u32x2 w = {cvtpk(acc0[4 * q] + acc1[4 * q], acc0[4 * q + 1] + acc1[4 * q + 1]), cvtpk(acc0[4 * q + 2] + acc1[4 * q + 2], acc0[4 * q + 3] + acc1[4 * q + 3])};
;         *reinterpret_cast<u32x2*>(sp + ((q >> 1) * 64 + (q & 1) * 32) * 8) = w;
;       } }
; #pragma unroll
;     for (int r = 0; r < 16; ++r) { acc0[r] *= gC; acc1[r] *= gC; }
; #pragma unroll
;     for (int ks = 0; ks < 8; ks += 2) {
;       u32x4 w0, w1;
; #pragma unroll
;       for (int i = 0; i < 4; ++i) {
;         w0[i] = cvtpk(bf2f((u16)vf[ks][2 * i]) * (facF[ks] * facG[2 * i]), bf2f((u16)vf[ks][2 * i + 1]) * (facF[ks] * facG[2 * i + 1]));
;         w1[i] = cvtpk(bf2f((u16)vf[ks + 1][2 * i]) * (facF[ks + 1] * facG[2 * i]), bf2f((u16)vf[ks + 1][2 * i + 1]) * (facF[ks + 1] * facG[2 * i + 1]));
;       }
;       __builtin_amdgcn_s_setprio(1);
;       acc0 = __builtin_amdgcn_mfma_f32_32x32x16_bf16(kf[ks], *reinterpret_cast<bf16x8*>(&w0), acc0, 0, 0, 0);
;       acc1 = __builtin_amdgcn_mfma_f32_32x32x16_bf16(kf[ks + 1], *reinterpret_cast<bf16x8*>(&w1), acc1, 0, 0, 0);
;       __builtin_amdgcn_s_setprio(0);
;     }
.LBB0_115:
	s_cmp_gt_u32 s5, 1
	s_cselect_b32 s7, 35, 1
	s_add_i32 s7, s7, s4
	s_sub_i32 s7, s7, 34
	s_and_b64 s[8:9], s[0:1], exec
	s_cselect_b32 s8, s7, s5
	s_ashr_i32 s9, s8, 31
	v_add_f32_e32 v166, v0, v16
	v_add_f32_e32 v167, v1, v17
	s_lshl_b64 s[8:9], s[8:9], 17
	v_cvt_pk_bf16_f32 v166, v166, v167
	v_add_f32_e32 v167, v2, v18
	v_lshl_add_u64 v[164:165], v[172:173], 0, s[8:9]
	v_add_f32_e32 v171, v3, v19
	v_cvt_pk_bf16_f32 v167, v167, v171
	global_store_dwordx2 v[164:165], v[166:167], off
	v_add_f32_e32 v166, v4, v20
	v_add_f32_e32 v167, v5, v21
	v_cvt_pk_bf16_f32 v166, v166, v167
	v_add_f32_e32 v167, v6, v22
	v_add_f32_e32 v171, v7, v23
	v_cvt_pk_bf16_f32 v167, v167, v171
	global_store_dwordx2 v[164:165], v[166:167], off offset:512
	v_add_f32_e32 v166, v8, v24
	v_add_f32_e32 v167, v9, v25
	v_cvt_pk_bf16_f32 v166, v166, v167
	v_add_f32_e32 v167, v10, v26
	v_add_f32_e32 v171, v11, v27
	v_cvt_pk_bf16_f32 v167, v167, v171
	global_store_dwordx2 v[164:165], v[166:167], off offset:1024
	v_add_f32_e32 v166, v12, v28
	v_add_f32_e32 v167, v13, v29
	v_cvt_pk_bf16_f32 v166, v166, v167
	v_add_f32_e32 v167, v14, v30
	v_add_f32_e32 v171, v15, v31
	v_cvt_pk_bf16_f32 v167, v167, v171
	global_store_dwordx2 v[164:165], v[166:167], off offset:1536
	v_lshlrev_b32_e32 v164, 16, v116
	v_and_b32_e32 v116, 0xffff0000, v116
	v_mul_f32_e32 v164, v162, v164
	v_mul_f32_e32 v116, v176, v116
	v_cvt_pk_bf16_f32 v116, v164, v116
	v_lshlrev_b32_e32 v164, 16, v104
	v_and_b32_e32 v104, 0xffff0000, v104
	v_mul_f32_e32 v164, v177, v164
	v_mul_f32_e32 v104, v178, v104
	v_cvt_pk_bf16_f32 v104, v164, v104
	v_lshlrev_b32_e32 v164, 16, v117
	v_and_b32_e32 v117, 0xffff0000, v117
	v_mul_f32_e32 v164, v179, v164
	v_mul_f32_e32 v117, v180, v117
	v_cvt_pk_bf16_f32 v117, v164, v117
	v_lshlrev_b32_e32 v164, 16, v105
	v_and_b32_e32 v105, 0xffff0000, v105
	v_mul_f32_e32 v164, v181, v164
	v_mul_f32_e32 v105, v182, v105
	v_cvt_pk_bf16_f32 v105, v164, v105
	v_lshlrev_b32_e32 v164, 16, v118
	v_and_b32_e32 v118, 0xffff0000, v118
	v_mul_f32_e32 v164, v183, v164
	v_mul_f32_e32 v118, v184, v118
	v_cvt_pk_bf16_f32 v118, v164, v118
	v_lshlrev_b32_e32 v164, 16, v106
	v_and_b32_e32 v106, 0xffff0000, v106
	v_mul_f32_e32 v164, v185, v164
	v_mul_f32_e32 v106, v198, v106
	v_cvt_pk_bf16_f32 v106, v164, v106
	v_lshlrev_b32_e32 v164, 16, v119
	v_and_b32_e32 v119, 0xffff0000, v119
	v_mul_f32_e32 v164, v199, v164
	v_mul_f32_e32 v119, v200, v119
	v_mov_b32_e32 v171, v170
	v_cvt_pk_bf16_f32 v119, v164, v119
	v_lshlrev_b32_e32 v164, 16, v107
	v_and_b32_e32 v107, 0xffff0000, v107
	v_pk_mul_f32 v[14:15], v[170:171], v[14:15]
	v_pk_mul_f32 v[12:13], v[170:171], v[12:13]
	v_pk_mul_f32 v[10:11], v[170:171], v[10:11]
	v_pk_mul_f32 v[8:9], v[170:171], v[8:9]
	v_pk_mul_f32 v[6:7], v[170:171], v[6:7]
	v_pk_mul_f32 v[4:5], v[170:171], v[4:5]
	v_pk_mul_f32 v[2:3], v[170:171], v[2:3]
	v_pk_mul_f32 v[0:1], v[174:175], v[0:1]
	v_pk_mul_f32 v[30:31], v[170:171], v[30:31]
	v_pk_mul_f32 v[28:29], v[170:171], v[28:29]
	v_pk_mul_f32 v[26:27], v[170:171], v[26:27]
	v_pk_mul_f32 v[24:25], v[170:171], v[24:25]
	v_pk_mul_f32 v[22:23], v[170:171], v[22:23]
	v_pk_mul_f32 v[20:21], v[170:171], v[20:21]
	v_pk_mul_f32 v[18:19], v[170:171], v[18:19]
	v_pk_mul_f32 v[16:17], v[174:175], v[16:17]
	v_mul_f32_e32 v107, v202, v107
	v_mul_f32_e32 v164, v201, v164
	v_cvt_pk_bf16_f32 v107, v164, v107
	s_setprio 1
	v_mfma_f32_32x32x16_bf16 v[0:15], v[80:83], v[116:119], v[0:15]
	v_mfma_f32_32x32x16_bf16 v[16:31], v[84:87], v[104:107], v[16:31]
	s_setprio 0
	v_lshlrev_b32_e32 v80, 16, v76
	v_and_b32_e32 v76, 0xffff0000, v76
	v_mul_f32_e32 v80, v203, v80
	v_mul_f32_e32 v76, v204, v76
	v_cvt_pk_bf16_f32 v76, v80, v76
	v_lshlrev_b32_e32 v80, 16, v72
	v_and_b32_e32 v72, 0xffff0000, v72
	v_mul_f32_e32 v80, v205, v80
	v_mul_f32_e32 v72, v206, v72
	v_cvt_pk_bf16_f32 v72, v80, v72
	v_lshlrev_b32_e32 v80, 16, v77
	v_and_b32_e32 v77, 0xffff0000, v77
	v_mul_f32_e32 v80, v207, v80
	v_mul_f32_e32 v77, v208, v77
	v_cvt_pk_bf16_f32 v77, v80, v77
	v_lshlrev_b32_e32 v80, 16, v73
	v_and_b32_e32 v73, 0xffff0000, v73
	v_mul_f32_e32 v80, v209, v80
	v_mul_f32_e32 v73, v210, v73
	v_cvt_pk_bf16_f32 v73, v80, v73
	v_lshlrev_b32_e32 v80, 16, v78
	v_and_b32_e32 v78, 0xffff0000, v78
	v_mul_f32_e32 v80, v211, v80
	v_mul_f32_e32 v78, v212, v78
	v_cvt_pk_bf16_f32 v78, v80, v78
	v_lshlrev_b32_e32 v80, 16, v74
	v_and_b32_e32 v74, 0xffff0000, v74
	v_mul_f32_e32 v80, v213, v80
	v_mul_f32_e32 v74, v214, v74
	v_cvt_pk_bf16_f32 v74, v80, v74
	v_lshlrev_b32_e32 v80, 16, v79
	v_and_b32_e32 v79, 0xffff0000, v79
	v_mul_f32_e32 v80, v215, v80
	v_mul_f32_e32 v79, v216, v79
	v_cvt_pk_bf16_f32 v79, v80, v79
	v_lshlrev_b32_e32 v80, 16, v75
	v_and_b32_e32 v75, 0xffff0000, v75
	v_mul_f32_e32 v80, v217, v80
	v_mul_f32_e32 v75, v218, v75
	v_cvt_pk_bf16_f32 v75, v80, v75
	s_setprio 1
	v_mfma_f32_32x32x16_bf16 v[0:15], v[64:67], v[76:79], v[0:15]
	v_mfma_f32_32x32x16_bf16 v[16:31], v[68:71], v[72:75], v[16:31]
	s_setprio 0
	v_lshlrev_b32_e32 v64, 16, v56
	v_and_b32_e32 v56, 0xffff0000, v56
	v_mul_f32_e32 v64, v219, v64
	v_mul_f32_e32 v56, v220, v56
	v_cvt_pk_bf16_f32 v56, v64, v56
	v_lshlrev_b32_e32 v64, 16, v60
	v_and_b32_e32 v60, 0xffff0000, v60
	v_mul_f32_e32 v64, v221, v64
	v_mul_f32_e32 v60, v222, v60
	v_cvt_pk_bf16_f32 v60, v64, v60
	v_lshlrev_b32_e32 v64, 16, v57
	v_and_b32_e32 v57, 0xffff0000, v57
	v_mul_f32_e32 v64, v223, v64
	v_mul_f32_e32 v57, v224, v57
	v_cvt_pk_bf16_f32 v57, v64, v57
	v_lshlrev_b32_e32 v64, 16, v61
	v_and_b32_e32 v61, 0xffff0000, v61
	v_mul_f32_e32 v64, v225, v64
	v_mul_f32_e32 v61, v226, v61
	v_cvt_pk_bf16_f32 v61, v64, v61
; DEV float bf2f(u16 h) { return __uint_as_float(((unsigned)h) << 16); }
; DEV unsigned cvtpk(float lo, float hi) { unsigned r; asm("v_cvt_pk_bf16_f32 %0, %1, %2" : "=v"(r) : "v"(lo), "v"(hi)); return r; }
; DEV void chain_item(const Params& p, int l, int item) {
;     ...
;     bf16x8 kf[8], vf[8];
; #pragma unroll
;     for (int ks = 0; ks < 8; ++ks) { kf[ks] = kfn[ks]; vf[ks] = vfn[ks]; }
;     if (s + 1 < 34) { const int s1 = s + 1; const int cn = (dir == 0) ? s1 : (s1 < 2 ? 1 - s1 : 35 - s1);
; #pragma unroll
;       for (int ks = 0; ks < 8; ++ks) { kfn[ks] = *reinterpret_cast<const bf16x8*>(KTf + (size_t)cn * 32768 + ks * 512); vfn[ks] = *reinterpret_cast<const bf16x8*>(VTf + (size_t)cn * 32768 + ks * 512); } }
;     { u16* sp = ST + (size_t)cid * 65536 + ((size_t)(sl * 16 + 2 * wid) * 64 + r32) * 8 + 4 * hi;
; #pragma unroll
;       for (int q = 0; q < 4; ++q) {
;         u32x2 w = {cvtpk(acc0[4 * q] + acc1[4 * q], acc0[4 * q + 1] + acc1[4 * q + 1]), cvtpk(acc0[4 * q + 2] + acc1[4 * q + 2], acc0[4 * q + 3] + acc1[4 * q + 3])};
;         *reinterpret_cast<u32x2*>(sp + ((q >> 1) * 64 + (q & 1) * 32) * 8) = w;
;       } }
; #pragma unroll
;     for (int r = 0; r < 16; ++r) { acc0[r] *= gC; acc1[r] *= gC; }
; #pragma unroll
;     for (int ks = 0; ks < 8; ks += 2) {
;       u32x4 w0, w1;
; #pragma unroll
;       for (int i = 0; i < 4; ++i) {
;         w0[i] = cvtpk(bf2f((u16)vf[ks][2 * i]) * (facF[ks] * facG[2 * i]), bf2f((u16)vf[ks][2 * i + 1]) * (facF[ks] * facG[2 * i + 1]));
;         w1[i] = cvtpk(bf2f((u16)vf[ks + 1][2 * i]) * (facF[ks + 1] * facG[2 * i]), bf2f((u16)vf[ks + 1][2 * i + 1]) * (facF[ks + 1] * facG[2 * i + 1]));
;       }
;       __builtin_amdgcn_s_setprio(1);
;       acc0 = __builtin_amdgcn_mfma_f32_32x32x16_bf16(kf[ks], *reinterpret_cast<bf16x8*>(&w0), acc0, 0, 0, 0);
;       acc1 = __builtin_amdgcn_mfma_f32_32x32x16_bf16(kf[ks + 1], *reinterpret_cast<bf16x8*>(&w1), acc1, 0, 0, 0);
;       __builtin_amdgcn_s_setprio(0);
;     }
	v_lshlrev_b32_e32 v64, 16, v58
	v_and_b32_e32 v58, 0xffff0000, v58
	v_mul_f32_e32 v64, v227, v64
	v_mul_f32_e32 v58, v228, v58
	v_cvt_pk_bf16_f32 v58, v64, v58
	v_lshlrev_b32_e32 v64, 16, v62
	v_and_b32_e32 v62, 0xffff0000, v62
	v_mul_f32_e32 v64, v229, v64
	v_mul_f32_e32 v62, v230, v62
	v_cvt_pk_bf16_f32 v62, v64, v62
	v_lshlrev_b32_e32 v64, 16, v59
	v_and_b32_e32 v59, 0xffff0000, v59
	v_mul_f32_e32 v64, v231, v64
	v_mul_f32_e32 v59, v232, v59
	v_cvt_pk_bf16_f32 v59, v64, v59
	v_lshlrev_b32_e32 v64, 16, v63
	v_and_b32_e32 v63, 0xffff0000, v63
	v_mul_f32_e32 v64, v233, v64
	v_mul_f32_e32 v63, v234, v63
	v_cvt_pk_bf16_f32 v63, v64, v63
	s_setprio 1
	v_mfma_f32_32x32x16_bf16 v[0:15], v[48:51], v[56:59], v[0:15]
	v_mfma_f32_32x32x16_bf16 v[16:31], v[52:55], v[60:63], v[16:31]
	s_setprio 0
	v_lshlrev_b32_e32 v48, 16, v44
	v_and_b32_e32 v44, 0xffff0000, v44
	v_mul_f32_e32 v48, v235, v48
	v_mul_f32_e32 v44, v236, v44
	v_cvt_pk_bf16_f32 v44, v48, v44
	v_lshlrev_b32_e32 v48, 16, v36
	v_and_b32_e32 v36, 0xffff0000, v36
	v_mul_f32_e32 v48, v237, v48
	v_mul_f32_e32 v36, v238, v36
	v_cvt_pk_bf16_f32 v36, v48, v36
	v_lshlrev_b32_e32 v48, 16, v45
	v_and_b32_e32 v45, 0xffff0000, v45
	v_mul_f32_e32 v48, v239, v48
	v_mul_f32_e32 v45, v240, v45
	v_cvt_pk_bf16_f32 v45, v48, v45
	v_lshlrev_b32_e32 v48, 16, v37
	v_and_b32_e32 v37, 0xffff0000, v37
	v_mul_f32_e32 v48, v241, v48
	v_mul_f32_e32 v37, v242, v37
	v_cvt_pk_bf16_f32 v37, v48, v37
	v_lshlrev_b32_e32 v48, 16, v46
	v_and_b32_e32 v46, 0xffff0000, v46
	v_mul_f32_e32 v48, v243, v48
	v_mul_f32_e32 v46, v244, v46
	v_cvt_pk_bf16_f32 v46, v48, v46
	v_lshlrev_b32_e32 v48, 16, v38
	v_and_b32_e32 v38, 0xffff0000, v38
	v_mul_f32_e32 v48, v245, v48
	v_mul_f32_e32 v38, v246, v38
	v_cvt_pk_bf16_f32 v38, v48, v38
	v_lshlrev_b32_e32 v48, 16, v47
	v_and_b32_e32 v47, 0xffff0000, v47
	v_mul_f32_e32 v48, v247, v48
	v_mul_f32_e32 v47, v248, v47
	v_cvt_pk_bf16_f32 v47, v48, v47
	v_lshlrev_b32_e32 v48, 16, v39
	v_and_b32_e32 v39, 0xffff0000, v39
	v_mul_f32_e32 v48, v249, v48
	v_mul_f32_e32 v39, v250, v39
	v_cvt_pk_bf16_f32 v39, v48, v39
	s_setprio 1
	v_mfma_f32_32x32x16_bf16 v[0:15], v[32:35], v[44:47], v[0:15]
	v_mfma_f32_32x32x16_bf16 v[16:31], v[40:43], v[36:39], v[16:31]
	s_setprio 0
	s_add_i32 s4, s4, -1
	s_waitcnt vmcnt(6)
	v_mov_b64_e32 v[36:37], v[136:137]
	v_mov_b64_e32 v[44:45], v[140:141]
	v_mov_b64_e32 v[60:61], v[128:129]
	v_mov_b64_e32 v[56:57], v[132:133]
	v_mov_b64_e32 v[72:73], v[108:109]
	v_mov_b64_e32 v[76:77], v[112:113]
	v_mov_b64_e32 v[106:107], v[94:95]
	v_mov_b64_e32 v[118:119], v[98:99]
	v_mov_b64_e32 v[80:81], v[88:89]
	v_mov_b64_e32 v[84:85], v[100:101]
	v_mov_b64_e32 v[64:65], v[120:121]
	v_mov_b64_e32 v[68:69], v[124:125]
	v_mov_b64_e32 v[48:49], v[144:145]
	v_mov_b64_e32 v[52:53], v[148:149]
	v_mov_b64_e32 v[32:33], v[152:153]
	v_mov_b64_e32 v[40:41], v[156:157]
	s_cmp_lg_u32 s4, 0
	v_mov_b64_e32 v[38:39], v[138:139]
	v_mov_b64_e32 v[46:47], v[142:143]
	v_mov_b64_e32 v[62:63], v[130:131]
	v_mov_b64_e32 v[58:59], v[134:135]
	v_mov_b64_e32 v[74:75], v[110:111]
	v_mov_b64_e32 v[78:79], v[114:115]
	v_mov_b64_e32 v[104:105], v[92:93]
	v_mov_b64_e32 v[116:117], v[96:97]
	v_mov_b64_e32 v[82:83], v[90:91]
	v_mov_b64_e32 v[86:87], v[102:103]
	v_mov_b64_e32 v[66:67], v[122:123]
	v_mov_b64_e32 v[70:71], v[126:127]
	v_mov_b64_e32 v[50:51], v[146:147]
	v_mov_b64_e32 v[54:55], v[150:151]
	v_mov_b64_e32 v[34:35], v[154:155]
	v_mov_b64_e32 v[42:43], v[158:159]
	s_mov_b32 s5, s6
	s_cbranch_scc0 .LBB0_113
.LBB0_116:
	s_add_i32 s6, s5, 1
	s_cmp_eq_u32 s4, 1
	s_cbranch_scc1 .LBB0_115
	s_cmp_lg_u32 s5, 0
	s_cselect_b32 s7, s4, 0
	s_and_b64 s[8:9], s[0:1], exec
	s_cselect_b32 s90, s7, s6
	s_lshl_b64 s[8:9], s[90:91], 16
	v_lshl_add_u64 v[128:129], v[168:169], 0, s[8:9]
	v_add_co_u32_e32 v136, vcc, s87, v128
	v_lshl_add_u64 v[130:131], v[160:161], 0, s[8:9]
	s_nop 0
	v_addc_co_u32_e32 v137, vcc, 0, v129, vcc
	v_add_co_u32_e32 v138, vcc, 0x1000, v130
	global_load_dwordx4 v[88:91], v[128:129], off
	global_load_dwordx4 v[100:103], v[128:129], off offset:1024
	global_load_dwordx4 v[96:99], v[130:131], off
	global_load_dwordx4 v[92:95], v[130:131], off offset:1024
	global_load_dwordx4 v[120:123], v[128:129], off offset:2048
	global_load_dwordx4 v[124:127], v[128:129], off offset:3072
	global_load_dwordx4 v[112:115], v[130:131], off offset:2048
	global_load_dwordx4 v[108:111], v[130:131], off offset:3072
	v_addc_co_u32_e32 v139, vcc, 0, v131, vcc
	global_load_dwordx4 v[144:147], v[136:137], off
	global_load_dwordx4 v[148:151], v[136:137], off offset:1024
	global_load_dwordx4 v[132:135], v[138:139], off
	global_load_dwordx4 v[128:131], v[138:139], off offset:1024
	global_load_dwordx4 v[152:155], v[136:137], off offset:2048
	global_load_dwordx4 v[156:159], v[136:137], off offset:3072
	global_load_dwordx4 v[140:143], v[138:139], off offset:2048
	s_nop 0
	global_load_dwordx4 v[136:139], v[138:139], off offset:3072
	s_and_b64 s[8:9], s[0:1], exec
	s_cbranch_scc0 .Lct_fwd
	s_add_i32 s8, s7, -1
	s_cmp_lt_u32 s7, 3
	s_cselect_b32 s8, s90, s8
	s_cmp_eq_u32 s5, 0
	s_cselect_b32 s7, 33, s8
	s_branch .Lct_go
.Lct_fwd:
	s_add_i32 s8, s6, 1
	s_cmp_gt_u32 s8, 33
	s_cselect_b32 s7, s90, s8
.Lct_go:
	s_lshl_b32 s7, s7, 16
	v_and_b32_e32 v166, 63, v252
	v_readfirstlane_b32 s8, v168
	v_readfirstlane_b32 s9, v169
	v_lshlrev_b32_e32 v166, 7, v166
	s_mov_b32 m0, 0
	s_nop 1
	s_add_u32 s8, s8, s7
	s_addc_u32 s9, s9, 0
	global_load_lds_dword v166, s[8:9]
	v_readfirstlane_b32 s8, v160
	v_readfirstlane_b32 s9, v161
	s_nop 3
	s_add_u32 s8, s8, s7
	s_addc_u32 s9, s9, 0
	global_load_lds_dword v166, s[8:9]
	s_branch .LBB0_115
